# P6 epilogue tail: 8 partial-sum load groups issued in one batch (dwordx4 sc1) with counted waits
# speedup vs baseline: 1.0164x; 1.0039x over previous
;     __device__ __forceinline__ void operator()(f32x4 (&acc)[2][2][4][2], const Unit& u, int wr, int wc, int fr, int fq) const {
;     ...
; #pragma unroll
;         for (int ai = 0; ai < 2; ++ai)
; #pragma unroll
;             for (int m = 0; m < 4; ++m) { const size_t r = (size_t)(row0 + ai * HALF + m * 16);
;                 const float* pp = ssq + r * 16 + 4 * fq + dep0;
;                 const float q0 = __hip_atomic_load(pp + 0, __ATOMIC_RELAXED, __HIP_MEMORY_SCOPE_AGENT), q1 = __hip_atomic_load(pp + 1, __ATOMIC_RELAXED, __HIP_MEMORY_SCOPE_AGENT),
;                             q2 = __hip_atomic_load(pp + 2, __ATOMIC_RELAXED, __HIP_MEMORY_SCOPE_AGENT), q3 = __hip_atomic_load(pp + 3, __ATOMIC_RELAXED, __HIP_MEMORY_SCOPE_AGENT);
;                 float tot = (q0 + q1) + (q2 + q3); tot += __shfl_xor(tot, 16); tot += __shfl_xor(tot, 32);
;                 const float rs = __builtin_amdgcn_rsqf(tot * (1.f / DM) + RMS_EPS);
; #pragma unroll
;                 for (int bj = 0; bj < 2; ++bj) { const size_t off = r * DM + col0 + bj * HALF;
;                     *(f32x4*)(out + off) = acc[ai][bj][m][0] * rs * gv[bj][0]; *(f32x4*)(out + off + 4) = acc[ai][bj][m][1] * rs * gv[bj][1]; } }
.LBB0_458:
	s_lshr_b32 s6, s6, 29
	v_lshlrev_b64 v[86:87], 2, v[178:179]
	v_lshl_add_u64 v[178:179], v[160:161], 0, v[188:189]
	s_and_b32 s6, s6, 4
	v_lshl_add_u64 v[8:9], s[18:19], 0, v[86:87]
	v_lshl_add_u64 v[178:179], v[178:179], 0, s[6:7]
	global_load_dwordx4 v[4:7], v[8:9], off offset:16
	global_load_dwordx4 v[12:15], v[8:9], off
	s_waitcnt lgkmcnt(0)
	global_load_dwordx4 v[0:3], v[8:9], off offset:528
	s_nop 0
	global_load_dwordx4 v[8:11], v[8:9], off offset:512
	s_nop 0
	global_load_dwordx4 v[212:215], v[178:179], off sc1
	global_load_dwordx4 v[216:219], v[178:179], off offset:1024 sc1
	global_load_dwordx4 v[220:223], v[178:179], off offset:2048 sc1
	global_load_dwordx4 v[224:227], v[178:179], off offset:3072 sc1
	s_mov_b64 s[60:61], 0x2000
	v_lshl_add_u64 v[244:245], v[178:179], 0, s[60:61]
	global_load_dwordx4 v[228:231], v[244:245], off sc1
	global_load_dwordx4 v[232:235], v[244:245], off offset:1024 sc1
	global_load_dwordx4 v[236:239], v[244:245], off offset:2048 sc1
	global_load_dwordx4 v[240:243], v[244:245], off offset:3072 sc1
	v_lshlrev_b64 v[176:177], 12, v[176:177]
	v_lshl_add_u64 v[176:177], s[20:21], 0, v[176:177]
	v_lshl_add_u64 v[176:177], v[176:177], 0, v[86:87]
	v_lshl_add_u64 v[82:83], v[160:161], 0, v[82:83]
	v_lshl_add_u64 v[82:83], v[82:83], 0, s[6:7]
	s_andn2_b64 vcc, exec, s[4:5]
	s_mov_b64 s[4:5], -1
	s_waitcnt vmcnt(7)
	s_nop 1
	v_mov_b32_e32 v188, v212
	v_mov_b32_e32 v208, v213
	v_mov_b32_e32 v189, v214
	v_mov_b32_e32 v209, v215
	v_pk_add_f32 v[178:179], v[188:189], v[208:209]
	s_nop 0
	v_add_f32_e32 v178, v178, v179
	ds_bpermute_b32 v179, v206, v178
	s_waitcnt lgkmcnt(0)
	v_add_f32_e32 v188, v178, v179
	ds_bpermute_b32 v189, v207, v188
	v_lshl_add_u64 v[178:179], v[160:161], 0, v[190:191]
	v_lshl_add_u64 v[178:179], v[178:179], 0, s[6:7]
	s_waitcnt lgkmcnt(0)
	v_add_f32_e32 v188, v188, v189
	v_fmamk_f32 v188, v188, 0x3a800000, v205
	v_rsq_f32_e32 v188, v188
	s_nop 0
	v_pk_mul_f32 v[124:125], v[124:125], v[188:189] op_sel_hi:[1,0]
	v_pk_mul_f32 v[126:127], v[126:127], v[188:189] op_sel_hi:[1,0]
	v_pk_mul_f32 v[120:121], v[120:121], v[188:189] op_sel_hi:[1,0]
	v_pk_mul_f32 v[122:123], v[122:123], v[188:189] op_sel_hi:[1,0]
	v_pk_mul_f32 v[190:191], v[116:117], v[188:189] op_sel_hi:[1,0]
	v_pk_mul_f32 v[208:209], v[118:119], v[188:189] op_sel_hi:[1,0]
	v_pk_mul_f32 v[210:211], v[112:113], v[188:189] op_sel_hi:[1,0]
	v_pk_mul_f32 v[188:189], v[114:115], v[188:189] op_sel_hi:[1,0]
	v_pk_mul_f32 v[114:115], v[14:15], v[126:127]
	v_pk_mul_f32 v[112:113], v[12:13], v[124:125]
	v_pk_mul_f32 v[118:119], v[6:7], v[122:123]
	v_pk_mul_f32 v[116:117], v[4:5], v[120:121]
	v_pk_mul_f32 v[122:123], v[10:11], v[208:209]
	v_pk_mul_f32 v[120:121], v[8:9], v[190:191]
	v_pk_mul_f32 v[126:127], v[2:3], v[188:189]
	v_pk_mul_f32 v[124:125], v[0:1], v[210:211]
	global_store_dwordx4 v[176:177], v[112:115], off
	global_store_dwordx4 v[176:177], v[116:119], off offset:16
	global_store_dwordx4 v[176:177], v[120:123], off offset:512
	global_store_dwordx4 v[176:177], v[124:127], off offset:528
	s_waitcnt vmcnt(10)
	s_nop 1
	v_mov_b32_e32 v112, v216
	v_mov_b32_e32 v114, v217
	v_mov_b32_e32 v113, v218
	v_mov_b32_e32 v115, v219
	v_pk_add_f32 v[112:113], v[112:113], v[114:115]
	s_nop 0
	v_add_f32_e32 v112, v112, v113
	ds_bpermute_b32 v113, v206, v112
	v_lshl_add_u64 v[114:115], v[160:161], 0, v[192:193]
	v_lshl_add_u64 v[122:123], v[114:115], 0, s[6:7]
	s_waitcnt lgkmcnt(0)
	v_add_f32_e32 v116, v112, v113
	ds_bpermute_b32 v117, v207, v116
	v_lshlrev_b64 v[112:113], 12, v[174:175]
	v_lshl_add_u64 v[112:113], s[20:21], 0, v[112:113]
	v_lshl_add_u64 v[120:121], v[112:113], 0, v[86:87]
	s_waitcnt lgkmcnt(0)
	v_add_f32_e32 v116, v116, v117
	v_fmamk_f32 v116, v116, 0x3a800000, v205
	v_rsq_f32_e32 v116, v116
	s_nop 0
	v_pk_mul_f32 v[108:109], v[108:109], v[116:117] op_sel_hi:[1,0]
	v_pk_mul_f32 v[110:111], v[110:111], v[116:117] op_sel_hi:[1,0]
	v_pk_mul_f32 v[112:113], v[104:105], v[116:117] op_sel_hi:[1,0]
	v_pk_mul_f32 v[114:115], v[106:107], v[116:117] op_sel_hi:[1,0]
	v_pk_mul_f32 v[118:119], v[146:147], v[116:117] op_sel_hi:[1,0]
	v_pk_mul_f32 v[124:125], v[144:145], v[116:117] op_sel_hi:[1,0]
	v_pk_mul_f32 v[126:127], v[150:151], v[116:117] op_sel_hi:[1,0]
	v_pk_mul_f32 v[116:117], v[148:149], v[116:117] op_sel_hi:[1,0]
	v_pk_mul_f32 v[106:107], v[14:15], v[110:111]
	v_pk_mul_f32 v[104:105], v[12:13], v[108:109]
	v_pk_mul_f32 v[110:111], v[6:7], v[114:115]
	v_pk_mul_f32 v[108:109], v[4:5], v[112:113]
	v_pk_mul_f32 v[114:115], v[10:11], v[124:125]
	v_pk_mul_f32 v[112:113], v[8:9], v[118:119]
	v_pk_mul_f32 v[118:119], v[2:3], v[116:117]
	v_pk_mul_f32 v[116:117], v[0:1], v[126:127]
	global_store_dwordx4 v[120:121], v[104:107], off
	global_store_dwordx4 v[120:121], v[108:111], off offset:16
	global_store_dwordx4 v[120:121], v[112:115], off offset:512
	global_store_dwordx4 v[120:121], v[116:119], off offset:528
	s_waitcnt vmcnt(13)
	s_nop 1
	v_mov_b32_e32 v104, v220
	v_mov_b32_e32 v106, v221
	v_mov_b32_e32 v105, v222
	v_mov_b32_e32 v107, v223
	v_pk_add_f32 v[104:105], v[104:105], v[106:107]
	s_nop 0
	v_add_f32_e32 v104, v104, v105
	ds_bpermute_b32 v105, v206, v104
	v_lshl_add_u64 v[106:107], v[160:161], 0, v[194:195]
	v_lshl_add_u64 v[116:117], v[106:107], 0, s[6:7]
	s_waitcnt lgkmcnt(0)
	v_add_f32_e32 v108, v104, v105
	ds_bpermute_b32 v109, v207, v108
	v_lshlrev_b64 v[104:105], 12, v[172:173]
	v_lshl_add_u64 v[104:105], s[20:21], 0, v[104:105]
	v_lshl_add_u64 v[114:115], v[104:105], 0, v[86:87]
	s_waitcnt lgkmcnt(0)
;     __device__ __forceinline__ void operator()(f32x4 (&acc)[2][2][4][2], const Unit& u, int wr, int wc, int fr, int fq) const {
;     ...
;             for (int m = 0; m < 4; ++m) { const size_t r = (size_t)(row0 + ai * HALF + m * 16);
;                 const float* pp = ssq + r * 16 + 4 * fq + dep0;
;                 const float q0 = __hip_atomic_load(pp + 0, __ATOMIC_RELAXED, __HIP_MEMORY_SCOPE_AGENT), q1 = __hip_atomic_load(pp + 1, __ATOMIC_RELAXED, __HIP_MEMORY_SCOPE_AGENT),
;                             q2 = __hip_atomic_load(pp + 2, __ATOMIC_RELAXED, __HIP_MEMORY_SCOPE_AGENT), q3 = __hip_atomic_load(pp + 3, __ATOMIC_RELAXED, __HIP_MEMORY_SCOPE_AGENT);
;                 float tot = (q0 + q1) + (q2 + q3); tot += __shfl_xor(tot, 16); tot += __shfl_xor(tot, 32);
;                 const float rs = __builtin_amdgcn_rsqf(tot * (1.f / DM) + RMS_EPS);
; #pragma unroll
;                 for (int bj = 0; bj < 2; ++bj) { const size_t off = r * DM + col0 + bj * HALF;
;                     *(f32x4*)(out + off) = acc[ai][bj][m][0] * rs * gv[bj][0]; *(f32x4*)(out + off + 4) = acc[ai][bj][m][1] * rs * gv[bj][1]; } }
	v_add_f32_e32 v108, v108, v109
	v_fmamk_f32 v108, v108, 0x3a800000, v205
	v_rsq_f32_e32 v108, v108
	s_nop 0
	v_pk_mul_f32 v[104:105], v[96:97], v[108:109] op_sel_hi:[1,0]
	v_pk_mul_f32 v[94:95], v[94:95], v[108:109] op_sel_hi:[1,0]
	v_pk_mul_f32 v[102:103], v[102:103], v[108:109] op_sel_hi:[1,0]
	v_pk_mul_f32 v[98:99], v[98:99], v[108:109] op_sel_hi:[1,0]
	v_pk_mul_f32 v[106:107], v[140:141], v[108:109] op_sel_hi:[1,0]
	v_pk_mul_f32 v[110:111], v[138:139], v[108:109] op_sel_hi:[1,0]
	v_pk_mul_f32 v[118:119], v[180:181], v[108:109] op_sel_hi:[1,0]
	v_pk_mul_f32 v[112:113], v[142:143], v[108:109] op_sel_hi:[1,0]
	v_pk_mul_f32 v[96:97], v[14:15], v[94:95]
	v_pk_mul_f32 v[94:95], v[12:13], v[104:105]
	v_pk_mul_f32 v[104:105], v[6:7], v[98:99]
	v_pk_mul_f32 v[102:103], v[4:5], v[102:103]
	v_pk_mul_f32 v[108:109], v[10:11], v[110:111]
	v_pk_mul_f32 v[106:107], v[8:9], v[106:107]
	v_pk_mul_f32 v[112:113], v[2:3], v[112:113]
	v_pk_mul_f32 v[110:111], v[0:1], v[118:119]
	global_store_dwordx4 v[114:115], v[94:97], off
	global_store_dwordx4 v[114:115], v[102:105], off offset:16
	global_store_dwordx4 v[114:115], v[106:109], off offset:512
	global_store_dwordx4 v[114:115], v[110:113], off offset:528
	s_waitcnt vmcnt(16)
	s_nop 1
	v_mov_b32_e32 v94, v224
	v_mov_b32_e32 v96, v225
	v_mov_b32_e32 v95, v226
	v_mov_b32_e32 v97, v227
	v_pk_add_f32 v[94:95], v[94:95], v[96:97]
	s_nop 0
	v_add_f32_e32 v94, v94, v95
	ds_bpermute_b32 v95, v206, v94
	v_lshl_add_u64 v[96:97], v[160:161], 0, v[196:197]
	v_lshl_add_u64 v[112:113], v[96:97], 0, s[6:7]
	s_waitcnt lgkmcnt(0)
	v_add_f32_e32 v98, v94, v95
	ds_bpermute_b32 v99, v207, v98
	v_lshlrev_b64 v[94:95], 12, v[170:171]
	v_lshl_add_u64 v[94:95], s[20:21], 0, v[94:95]
	v_lshl_add_u64 v[110:111], v[94:95], 0, v[86:87]
	s_waitcnt lgkmcnt(0)
	v_add_f32_e32 v98, v98, v99
	v_fmamk_f32 v98, v98, 0x3a800000, v205
	v_rsq_f32_e32 v98, v98
	s_nop 0
	v_pk_mul_f32 v[94:95], v[132:133], v[98:99] op_sel_hi:[1,0]
	v_pk_mul_f32 v[96:97], v[100:101], v[98:99] op_sel_hi:[1,0]
	v_pk_mul_f32 v[102:103], v[136:137], v[98:99] op_sel_hi:[1,0]
	v_pk_mul_f32 v[100:101], v[134:135], v[98:99] op_sel_hi:[1,0]
	v_pk_mul_f32 v[106:107], v[130:131], v[98:99] op_sel_hi:[1,0]
	v_pk_mul_f32 v[104:105], v[128:129], v[98:99] op_sel_hi:[1,0]
	v_pk_mul_f32 v[114:115], v[184:185], v[98:99] op_sel_hi:[1,0]
	v_pk_mul_f32 v[108:109], v[182:183], v[98:99] op_sel_hi:[1,0]
	v_pk_mul_f32 v[96:97], v[14:15], v[96:97]
	v_pk_mul_f32 v[94:95], v[12:13], v[94:95]
	v_pk_mul_f32 v[100:101], v[6:7], v[100:101]
	v_pk_mul_f32 v[98:99], v[4:5], v[102:103]
	v_pk_mul_f32 v[104:105], v[10:11], v[104:105]
	v_pk_mul_f32 v[102:103], v[8:9], v[106:107]
	v_pk_mul_f32 v[108:109], v[2:3], v[108:109]
	v_pk_mul_f32 v[106:107], v[0:1], v[114:115]
	global_store_dwordx4 v[110:111], v[94:97], off
	global_store_dwordx4 v[110:111], v[98:101], off offset:16
	global_store_dwordx4 v[110:111], v[102:105], off offset:512
	global_store_dwordx4 v[110:111], v[106:109], off offset:528
	s_waitcnt vmcnt(19)
	s_nop 1
	v_mov_b32_e32 v94, v228
	v_mov_b32_e32 v96, v229
	v_mov_b32_e32 v95, v230
	v_mov_b32_e32 v97, v231
	v_pk_add_f32 v[94:95], v[94:95], v[96:97]
	s_nop 0
	v_add_f32_e32 v94, v94, v95
	ds_bpermute_b32 v95, v206, v94
	s_waitcnt lgkmcnt(0)
	v_add_f32_e32 v96, v94, v95
	ds_bpermute_b32 v97, v207, v96
	v_lshlrev_b64 v[94:95], 12, v[186:187]
	v_lshl_add_u64 v[94:95], s[20:21], 0, v[94:95]
	v_lshl_add_u64 v[94:95], v[94:95], 0, v[86:87]
	s_waitcnt lgkmcnt(0)
	v_add_f32_e32 v96, v96, v97
	v_fmamk_f32 v96, v96, 0x3a800000, v205
	v_rsq_f32_e32 v96, v96
	s_nop 0
	v_pk_mul_f32 v[60:61], v[60:61], v[96:97] op_sel_hi:[1,0]
	v_pk_mul_f32 v[62:63], v[62:63], v[96:97] op_sel_hi:[1,0]
	v_pk_mul_f32 v[56:57], v[56:57], v[96:97] op_sel_hi:[1,0]
	v_pk_mul_f32 v[58:59], v[58:59], v[96:97] op_sel_hi:[1,0]
	v_pk_mul_f32 v[98:99], v[52:53], v[96:97] op_sel_hi:[1,0]
	v_pk_mul_f32 v[100:101], v[54:55], v[96:97] op_sel_hi:[1,0]
	v_pk_mul_f32 v[102:103], v[48:49], v[96:97] op_sel_hi:[1,0]
	v_pk_mul_f32 v[96:97], v[50:51], v[96:97] op_sel_hi:[1,0]
	v_pk_mul_f32 v[50:51], v[14:15], v[62:63]
	v_pk_mul_f32 v[48:49], v[12:13], v[60:61]
	v_pk_mul_f32 v[54:55], v[6:7], v[58:59]
	v_pk_mul_f32 v[52:53], v[4:5], v[56:57]
	v_pk_mul_f32 v[58:59], v[10:11], v[100:101]
	v_pk_mul_f32 v[56:57], v[8:9], v[98:99]
	v_pk_mul_f32 v[62:63], v[2:3], v[96:97]
	v_pk_mul_f32 v[60:61], v[0:1], v[102:103]
	global_store_dwordx4 v[94:95], v[48:51], off
	global_store_dwordx4 v[94:95], v[52:55], off offset:16
	global_store_dwordx4 v[94:95], v[56:59], off offset:512
	global_store_dwordx4 v[94:95], v[60:63], off offset:528
	s_waitcnt vmcnt(22)
	s_nop 1
	v_mov_b32_e32 v48, v232
	v_mov_b32_e32 v50, v233
	v_mov_b32_e32 v49, v234
	v_mov_b32_e32 v51, v235
	v_pk_add_f32 v[48:49], v[48:49], v[50:51]
	s_nop 0
	v_add_f32_e32 v48, v48, v49
	ds_bpermute_b32 v49, v206, v48
	v_lshl_add_u64 v[50:51], v[160:161], 0, v[78:79]
	v_lshl_add_u64 v[50:51], v[50:51], 0, s[6:7]
	s_waitcnt lgkmcnt(0)
;     __device__ __forceinline__ void operator()(f32x4 (&acc)[2][2][4][2], const Unit& u, int wr, int wc, int fr, int fq) const {
;     ...
;             for (int m = 0; m < 4; ++m) { const size_t r = (size_t)(row0 + ai * HALF + m * 16);
;                 const float* pp = ssq + r * 16 + 4 * fq + dep0;
;                 const float q0 = __hip_atomic_load(pp + 0, __ATOMIC_RELAXED, __HIP_MEMORY_SCOPE_AGENT), q1 = __hip_atomic_load(pp + 1, __ATOMIC_RELAXED, __HIP_MEMORY_SCOPE_AGENT),
;                             q2 = __hip_atomic_load(pp + 2, __ATOMIC_RELAXED, __HIP_MEMORY_SCOPE_AGENT), q3 = __hip_atomic_load(pp + 3, __ATOMIC_RELAXED, __HIP_MEMORY_SCOPE_AGENT);
;                 float tot = (q0 + q1) + (q2 + q3); tot += __shfl_xor(tot, 16); tot += __shfl_xor(tot, 32);
;                 const float rs = __builtin_amdgcn_rsqf(tot * (1.f / DM) + RMS_EPS);
; #pragma unroll
;                 for (int bj = 0; bj < 2; ++bj) { const size_t off = r * DM + col0 + bj * HALF;
;                     *(f32x4*)(out + off) = acc[ai][bj][m][0] * rs * gv[bj][0]; *(f32x4*)(out + off + 4) = acc[ai][bj][m][1] * rs * gv[bj][1]; } }
	v_add_f32_e32 v52, v48, v49
	ds_bpermute_b32 v53, v207, v52
	v_lshlrev_b64 v[48:49], 12, v[92:93]
	v_lshl_add_u64 v[48:49], s[20:21], 0, v[48:49]
	v_lshl_add_u64 v[54:55], v[48:49], 0, v[86:87]
	s_waitcnt lgkmcnt(0)
	v_add_f32_e32 v52, v52, v53
	v_fmamk_f32 v52, v52, 0x3a800000, v205
	v_rsq_f32_e32 v52, v52
	s_nop 0
	v_pk_mul_f32 v[44:45], v[44:45], v[52:53] op_sel_hi:[1,0]
	v_pk_mul_f32 v[46:47], v[46:47], v[52:53] op_sel_hi:[1,0]
	v_pk_mul_f32 v[48:49], v[40:41], v[52:53] op_sel_hi:[1,0]
	v_pk_mul_f32 v[40:41], v[42:43], v[52:53] op_sel_hi:[1,0]
	v_pk_mul_f32 v[42:43], v[36:37], v[52:53] op_sel_hi:[1,0]
	v_pk_mul_f32 v[56:57], v[38:39], v[52:53] op_sel_hi:[1,0]
	v_pk_mul_f32 v[58:59], v[80:81], v[52:53] op_sel_hi:[1,0]
	v_pk_mul_f32 v[52:53], v[34:35], v[52:53] op_sel_hi:[1,0]
	v_pk_mul_f32 v[36:37], v[14:15], v[46:47]
	v_pk_mul_f32 v[34:35], v[12:13], v[44:45]
	v_pk_mul_f32 v[40:41], v[6:7], v[40:41]
	v_pk_mul_f32 v[38:39], v[4:5], v[48:49]
	v_pk_mul_f32 v[44:45], v[10:11], v[56:57]
	v_pk_mul_f32 v[42:43], v[8:9], v[42:43]
	v_pk_mul_f32 v[48:49], v[2:3], v[52:53]
	v_pk_mul_f32 v[46:47], v[0:1], v[58:59]
	global_store_dwordx4 v[54:55], v[34:37], off
	global_store_dwordx4 v[54:55], v[38:41], off offset:16
	global_store_dwordx4 v[54:55], v[42:45], off offset:512
	global_store_dwordx4 v[54:55], v[46:49], off offset:528
	s_waitcnt vmcnt(25)
	s_nop 1
	v_mov_b32_e32 v34, v236
	v_mov_b32_e32 v36, v237
	v_mov_b32_e32 v35, v238
	v_mov_b32_e32 v37, v239
	v_pk_add_f32 v[34:35], v[34:35], v[36:37]
	s_nop 0
	v_add_f32_e32 v34, v34, v35
	ds_bpermute_b32 v35, v206, v34
	v_lshl_add_u64 v[36:37], v[160:161], 0, v[84:85]
	v_lshl_add_u64 v[42:43], v[36:37], 0, s[6:7]
	s_waitcnt lgkmcnt(0)
	v_add_f32_e32 v38, v34, v35
	ds_bpermute_b32 v39, v207, v38
	v_lshlrev_b64 v[34:35], 12, v[90:91]
	v_lshl_add_u64 v[34:35], s[20:21], 0, v[34:35]
	v_lshl_add_u64 v[40:41], v[34:35], 0, v[86:87]
	s_waitcnt lgkmcnt(0)
	v_add_f32_e32 v38, v38, v39
	v_fmamk_f32 v38, v38, 0x3a800000, v205
	v_rsq_f32_e32 v38, v38
	s_nop 0
	v_pk_mul_f32 v[28:29], v[28:29], v[38:39] op_sel_hi:[1,0]
	v_pk_mul_f32 v[30:31], v[30:31], v[38:39] op_sel_hi:[1,0]
	v_pk_mul_f32 v[34:35], v[24:25], v[38:39] op_sel_hi:[1,0]
	v_pk_mul_f32 v[36:37], v[26:27], v[38:39] op_sel_hi:[1,0]
	v_pk_mul_f32 v[44:45], v[72:73], v[38:39] op_sel_hi:[1,0]
	v_pk_mul_f32 v[32:33], v[32:33], v[38:39] op_sel_hi:[1,0]
	v_pk_mul_f32 v[46:47], v[76:77], v[38:39] op_sel_hi:[1,0]
	v_pk_mul_f32 v[38:39], v[74:75], v[38:39] op_sel_hi:[1,0]
	v_pk_mul_f32 v[26:27], v[14:15], v[30:31]
	v_pk_mul_f32 v[24:25], v[12:13], v[28:29]
	v_pk_mul_f32 v[30:31], v[6:7], v[36:37]
	v_pk_mul_f32 v[28:29], v[4:5], v[34:35]
	v_pk_mul_f32 v[34:35], v[10:11], v[32:33]
	v_pk_mul_f32 v[32:33], v[8:9], v[44:45]
	v_pk_mul_f32 v[38:39], v[2:3], v[38:39]
	v_pk_mul_f32 v[36:37], v[0:1], v[46:47]
	global_store_dwordx4 v[40:41], v[24:27], off
	global_store_dwordx4 v[40:41], v[28:31], off offset:16
	global_store_dwordx4 v[40:41], v[32:35], off offset:512
	global_store_dwordx4 v[40:41], v[36:39], off offset:528
	s_waitcnt vmcnt(28)
	s_nop 1
	v_mov_b32_e32 v24, v240
	v_mov_b32_e32 v26, v241
	v_mov_b32_e32 v25, v242
	v_mov_b32_e32 v27, v243
	v_pk_add_f32 v[24:25], v[24:25], v[26:27]
	s_nop 0
	v_add_f32_e32 v24, v24, v25
	ds_bpermute_b32 v25, v206, v24
	s_waitcnt lgkmcnt(0)
	v_add_f32_e32 v26, v24, v25
	ds_bpermute_b32 v27, v207, v26
	v_lshlrev_b64 v[24:25], 12, v[88:89]
	v_lshl_add_u64 v[24:25], s[20:21], 0, v[24:25]
	v_lshl_add_u64 v[24:25], v[24:25], 0, v[86:87]
	s_waitcnt lgkmcnt(0)
	v_add_f32_e32 v26, v26, v27
	v_fmamk_f32 v26, v26, 0x3a800000, v205
	v_rsq_f32_e32 v26, v26
	s_nop 0
	v_pk_mul_f32 v[18:19], v[18:19], v[26:27] op_sel_hi:[1,0]
	v_pk_mul_f32 v[16:17], v[16:17], v[26:27] op_sel_hi:[1,0]
	v_pk_mul_f32 v[22:23], v[22:23], v[26:27] op_sel_hi:[1,0]
	v_pk_mul_f32 v[20:21], v[20:21], v[26:27] op_sel_hi:[1,0]
	v_pk_mul_f32 v[28:29], v[66:67], v[26:27] op_sel_hi:[1,0]
	v_pk_mul_f32 v[30:31], v[64:65], v[26:27] op_sel_hi:[1,0]
	v_pk_mul_f32 v[32:33], v[70:71], v[26:27] op_sel_hi:[1,0]
	v_pk_mul_f32 v[26:27], v[68:69], v[26:27] op_sel_hi:[1,0]
	v_pk_mul_f32 v[14:15], v[14:15], v[16:17]
	v_pk_mul_f32 v[12:13], v[12:13], v[18:19]
	v_pk_mul_f32 v[6:7], v[6:7], v[20:21]
	v_pk_mul_f32 v[4:5], v[4:5], v[22:23]
	v_pk_mul_f32 v[10:11], v[10:11], v[30:31]
	v_pk_mul_f32 v[8:9], v[8:9], v[28:29]
	v_pk_mul_f32 v[2:3], v[2:3], v[26:27]
	v_pk_mul_f32 v[0:1], v[0:1], v[32:33]
	global_store_dwordx4 v[24:25], v[12:15], off
	global_store_dwordx4 v[24:25], v[4:7], off offset:16
	global_store_dwordx4 v[24:25], v[8:11], off offset:512
	global_store_dwordx4 v[24:25], v[0:3], off offset:528
	s_cbranch_vccnz .LBB0_423
	s_andn2_b64 vcc, exec, s[8:9]
	s_cbranch_vccnz .LBB0_422
	s_mov_b32 s100, 1
	s_branch .LBB0_422
